# MLA fast path regions B/C/D hand-scheduled: exp spread 2 per MFMA, exp(sub1) interleaved with PV(sub0), PV(sub1) V-fragment reads hoisted into spare VGPRs
# speedup vs baseline: 1.0402x; 1.0128x over previous
; #define MFMA(a, b, c) __builtin_amdgcn_mfma_f32_32x32x16_bf16((a), (b), (c), 0, 0, 0)
; template <bool DIFF>
; DI void attn_phase(const AttnArgs& a, char* lds) {
;     ...
;         {
;           s1 = MFMA(kf[0], qf[0], negm);
; #pragma unroll
;           for (int ds = 1; ds < NDS; ++ds) s1 = MFMA(kf[ds], qf[ds], s1);
;           float ps = 0.f;
; #pragma unroll
;           for (int r = 0; r < 16; ++r) { s0[r] = __builtin_amdgcn_exp2f(s0[r]); ps += s0[r]; }
;           l_sum += ps;
;           asm volatile("" : "+v"(l_sum));
; #pragma unroll
;           for (int i = 0; i < NDS; ++i) { __builtin_amdgcn_sched_group_barrier(0x008, 1, 0); __builtin_amdgcn_sched_group_barrier(0x002, 4, 0); }
;         }
;         __builtin_amdgcn_sched_barrier(0);
;         if (needmask) {
; #pragma unroll
;           for (int r = 0; r < 16; ++r) {
;             const int kl = 32 + ((r < 8) ? (8 * g2 + r) : (16 + 8 * g2 + (r - 8)));
;             if ((pki[kl] >> 6) > (((int)qposf) >> 6)) s1[r] = -__builtin_inff();
;           }
;         }
.LBB0_382:
	s_waitcnt lgkmcnt(0)
	v_mfma_f32_32x32x16_bf16 v[80:95], v[80:83], v[112:115], 0
	s_nop 6
	v_exp_f32_e32 v218, v96
	v_exp_f32_e32 v97, v97
	v_add_f32_e32 v96, 0, v218
	v_add_f32_e32 v96, v97, v96
	v_mfma_f32_32x32x16_bf16 v[80:95], v[204:207], v[116:119], v[80:95]
	v_exp_f32_e32 v98, v98
	v_exp_f32_e32 v99, v99
	v_add_f32_e32 v96, v98, v96
	v_add_f32_e32 v96, v99, v96
	v_mfma_f32_32x32x16_bf16 v[80:95], v[200:203], v[120:123], v[80:95]
	v_exp_f32_e32 v100, v100
	v_exp_f32_e32 v101, v101
	v_add_f32_e32 v96, v100, v96
	v_add_f32_e32 v96, v101, v96
	v_mfma_f32_32x32x16_bf16 v[80:95], v[196:199], v[124:127], v[80:95]
	v_exp_f32_e32 v102, v102
	v_exp_f32_e32 v204, v103
	v_add_f32_e32 v96, v102, v96
	v_add_f32_e32 v96, v204, v96
	v_mfma_f32_32x32x16_bf16 v[80:95], v[192:195], v[128:131], v[80:95]
	v_exp_f32_e32 v103, v104
	v_exp_f32_e32 v104, v105
	v_add_f32_e32 v96, v103, v96
	v_add_f32_e32 v96, v104, v96
	v_mfma_f32_32x32x16_bf16 v[80:95], v[184:187], v[132:135], v[80:95]
	v_exp_f32_e32 v105, v106
	v_exp_f32_e32 v106, v107
	v_add_f32_e32 v96, v105, v96
	v_add_f32_e32 v96, v106, v96
	v_mfma_f32_32x32x16_bf16 v[80:95], v[168:171], v[136:139], v[80:95]
	v_exp_f32_e32 v107, v108
	v_exp_f32_e32 v108, v109
	v_add_f32_e32 v96, v107, v96
	v_add_f32_e32 v96, v108, v96
	v_mfma_f32_32x32x16_bf16 v[80:95], v[188:191], v[140:143], v[80:95]
	v_exp_f32_e32 v109, v110
	v_exp_f32_e32 v110, v111
	v_add_f32_e32 v96, v109, v96
	v_add_f32_e32 v96, v110, v96
	v_add_f32_e32 v96, v217, v96
	v_mfma_f32_32x32x16_bf16 v[80:95], v[172:175], v[144:147], v[80:95]
	v_mfma_f32_32x32x16_bf16 v[80:95], v[176:179], v[148:151], v[80:95]
	v_mfma_f32_32x32x16_bf16 v[80:95], v[180:183], v[152:155], v[80:95]
	v_mfma_f32_32x32x16_bf16 v[80:95], v[164:167], v[156:159], v[80:95]
	s_and_b64 vcc, exec, s[10:11]
	s_cbranch_vccnz .LBB0_384
	ds_read_b128 v[164:167], v15 offset:41088
	ds_read_b128 v[168:171], v15 offset:41104
	s_waitcnt lgkmcnt(0)
	v_ashrrev_i32_e32 v111, 6, v164
	v_ashrrev_i32_e32 v164, 6, v165
	v_cmp_le_i32_e32 vcc, v111, v215
	v_ashrrev_i32_e32 v111, 6, v166
	s_nop 2
	v_cndmask_b32_e32 v80, v212, v80, vcc
	v_cmp_le_i32_e32 vcc, v164, v215
	s_nop 1
	v_cndmask_b32_e32 v81, v212, v81, vcc
	v_cmp_le_i32_e32 vcc, v111, v215
	v_ashrrev_i32_e32 v111, 6, v167
	ds_read_b128 v[164:167], v15 offset:41152
	v_cndmask_b32_e32 v82, v212, v82, vcc
	v_cmp_le_i32_e32 vcc, v111, v215
	v_ashrrev_i32_e32 v111, 6, v168
	s_nop 0
	v_cndmask_b32_e32 v83, v212, v83, vcc
	v_cmp_le_i32_e32 vcc, v111, v215
	v_ashrrev_i32_e32 v111, 6, v169
	s_nop 0
	v_cndmask_b32_e32 v84, v212, v84, vcc
	v_cmp_le_i32_e32 vcc, v111, v215
	v_ashrrev_i32_e32 v111, 6, v170
	s_nop 0
	v_cndmask_b32_e32 v85, v212, v85, vcc
	v_cmp_le_i32_e32 vcc, v111, v215
	v_ashrrev_i32_e32 v111, 6, v171
	ds_read_b128 v[168:171], v15 offset:41168
	v_cndmask_b32_e32 v86, v212, v86, vcc
	v_cmp_le_i32_e32 vcc, v111, v215
	s_waitcnt lgkmcnt(0)
	v_ashrrev_i32_e32 v15, 6, v164
	v_cndmask_b32_e32 v87, v212, v87, vcc
	v_cmp_le_i32_e32 vcc, v15, v215
	v_ashrrev_i32_e32 v15, 6, v165
	s_nop 0
	v_cndmask_b32_e32 v88, v212, v88, vcc
	v_cmp_le_i32_e32 vcc, v15, v215
	v_ashrrev_i32_e32 v15, 6, v166
	s_nop 0
	v_cndmask_b32_e32 v89, v212, v89, vcc
	v_cmp_le_i32_e32 vcc, v15, v215
	v_ashrrev_i32_e32 v15, 6, v167
	s_nop 0
	v_cndmask_b32_e32 v90, v212, v90, vcc
	v_cmp_le_i32_e32 vcc, v15, v215
	v_ashrrev_i32_e32 v15, 6, v168
	s_nop 0
	v_cndmask_b32_e32 v91, v212, v91, vcc
	v_cmp_le_i32_e32 vcc, v15, v215
	v_ashrrev_i32_e32 v15, 6, v169
	s_nop 0
	v_cndmask_b32_e32 v92, v212, v92, vcc
	v_cmp_le_i32_e32 vcc, v15, v215
	v_ashrrev_i32_e32 v15, 6, v170
	s_nop 0
	v_cndmask_b32_e32 v93, v212, v93, vcc
	v_cmp_le_i32_e32 vcc, v15, v215
	v_ashrrev_i32_e32 v15, 6, v171
	s_nop 0
	v_cndmask_b32_e32 v94, v212, v94, vcc
	v_cmp_le_i32_e32 vcc, v15, v215
	s_nop 1
	v_cndmask_b32_e32 v95, v212, v95, vcc
; #define MFMA(a, b, c) __builtin_amdgcn_mfma_f32_32x32x16_bf16((a), (b), (c), 0, 0, 0)
; DI u32 pk2(float a, float b) { f2_t v = {a, b}; bf2_t r = __builtin_convertvector(v, bf2_t); return __builtin_bit_cast(u32, r); }
; template <bool DIFF>
; DI void attn_phase(const AttnArgs& a, char* lds) {
;     ...
;         {
; #pragma unroll
;           for (int m = 0; m < NM; ++m) vf[1][m] = *(const bf16x8*)(sb + voffb + m * 4096 + ((2 ^ vx) << 4));
; #pragma unroll
;           for (int s2 = 0; s2 < 2; ++s2) {
;             u32x4 pw;
;             pw[0] = pk2(s0[8 * s2], s0[8 * s2 + 1]); pw[1] = pk2(s0[8 * s2 + 2], s0[8 * s2 + 3]);
;             pw[2] = pk2(s0[8 * s2 + 4], s0[8 * s2 + 5]); pw[3] = pk2(s0[8 * s2 + 6], s0[8 * s2 + 7]);
;             const bf16x8 pf = __builtin_bit_cast(bf16x8, pw);
;             __builtin_amdgcn_s_setprio(1);
; #pragma unroll
;             for (int m = 0; m < NM; ++m) o[m] = MFMA(vf[s2][m], pf, o[m]);
;             __builtin_amdgcn_s_setprio(0);
;           }
;           float ps = 0.f;
; #pragma unroll
;           for (int r = 0; r < 16; ++r) { s1[r] = __builtin_amdgcn_exp2f(s1[r]); ps += s1[r]; }
;           l_sum += ps;
;           asm volatile("" : "+v"(l_sum));
; #pragma unroll
;           for (int s2 = 0; s2 < 2; ++s2)
; #pragma unroll
;             for (int m = 0; m < NM; ++m) vf[s2][m] = *(const bf16x8*)(sb + voffb + m * 4096 + (((4 + 2 * s2) ^ vx) << 4));
;           __builtin_amdgcn_sched_group_barrier(0x002, 8, 0);
; #pragma unroll
;           for (int i = 0; i < 2 * NM; ++i) { __builtin_amdgcn_sched_group_barrier(0x008, 1, 0); __builtin_amdgcn_sched_group_barrier(0x002, 5, 0); }
;         }
;         __builtin_amdgcn_sched_barrier(0);
;         {
; #pragma unroll
;           for (int s2 = 0; s2 < 2; ++s2) {
;             u32x4 pw;
;             pw[0] = pk2(s1[8 * s2], s1[8 * s2 + 1]); pw[1] = pk2(s1[8 * s2 + 2], s1[8 * s2 + 3]);
;             pw[2] = pk2(s1[8 * s2 + 4], s1[8 * s2 + 5]); pw[3] = pk2(s1[8 * s2 + 6], s1[8 * s2 + 7]);
;             const bf16x8 pf = __builtin_bit_cast(bf16x8, pw);
;             __builtin_amdgcn_s_setprio(1);
; #pragma unroll
;             for (int m = 0; m < NM; ++m) o[m] = MFMA(vf[s2][m], pf, o[m]);
;             __builtin_amdgcn_s_setprio(0);
;           }
;         }
.LBB0_384:
	v_xad_u32 v15, v14, 32, v0
	ds_read_b128 v[164:167], v15 offset:24576
	ds_read_b128 v[168:171], v15 offset:28672
	ds_read_b128 v[172:175], v15 offset:32768
	ds_read_b128 v[176:179], v15 offset:36864
	v_cvt_pk_bf16_f32 v180, v218, v97
	v_cvt_pk_bf16_f32 v181, v98, v99
	v_cvt_pk_bf16_f32 v182, v100, v101
	v_cvt_pk_bf16_f32 v183, v102, v204
	v_cvt_pk_bf16_f32 v248, v103, v104
	v_cvt_pk_bf16_f32 v249, v105, v106
	v_cvt_pk_bf16_f32 v250, v107, v108
	v_cvt_pk_bf16_f32 v251, v109, v110
	v_xad_u32 v227, v14, 64, v0
	v_xad_u32 v0, v14, s82, v0
	v_mfma_f32_32x32x16_bf16 v[64:79], v[160:163], v[180:183], v[64:79]
	v_exp_f32_e32 v15, v80
	v_exp_f32_e32 v100, v81
	v_add_f32_e32 v252, 0, v15
	v_add_f32_e32 v252, v100, v252
	v_mfma_f32_32x32x16_bf16 v[48:63], v[10:13], v[180:183], v[48:63]
	v_exp_f32_e32 v101, v82
	v_exp_f32_e32 v102, v83
	v_add_f32_e32 v252, v101, v252
	v_add_f32_e32 v252, v102, v252
	v_mfma_f32_32x32x16_bf16 v[32:47], v[6:9], v[180:183], v[32:47]
	v_exp_f32_e32 v103, v84
	v_exp_f32_e32 v104, v85
	v_add_f32_e32 v252, v103, v252
	v_add_f32_e32 v252, v104, v252
	v_mfma_f32_32x32x16_bf16 v[16:31], v[2:5], v[180:183], v[16:31]
	ds_read_b128 v[2:5], v227 offset:24576
	ds_read_b128 v[6:9], v227 offset:28672
	ds_read_b128 v[10:13], v227 offset:32768
	ds_read_b128 v[228:231], v227 offset:36864
	v_exp_f32_e32 v105, v86
	v_exp_f32_e32 v106, v87
	v_add_f32_e32 v252, v105, v252
	v_add_f32_e32 v252, v106, v252
	s_waitcnt lgkmcnt(4)
	v_mfma_f32_32x32x16_bf16 v[64:79], v[164:167], v[248:251], v[64:79]
	ds_read_b128 v[232:235], v0 offset:24576
	ds_read_b128 v[236:239], v0 offset:28672
	ds_read_b128 v[240:243], v0 offset:32768
	ds_read_b128 v[244:247], v0 offset:36864
	v_exp_f32_e32 v107, v88
	v_exp_f32_e32 v108, v89
	v_add_f32_e32 v252, v107, v252
	v_add_f32_e32 v252, v108, v252
	v_mfma_f32_32x32x16_bf16 v[48:63], v[168:171], v[248:251], v[48:63]
	v_exp_f32_e32 v109, v90
	v_exp_f32_e32 v110, v91
	v_add_f32_e32 v252, v109, v252
	v_add_f32_e32 v252, v110, v252
	v_mfma_f32_32x32x16_bf16 v[32:47], v[172:175], v[248:251], v[32:47]
	v_exp_f32_e32 v111, v92
	v_exp_f32_e32 v160, v93
	v_add_f32_e32 v252, v111, v252
	v_add_f32_e32 v252, v160, v252
	v_mfma_f32_32x32x16_bf16 v[16:31], v[176:179], v[248:251], v[16:31]
	v_exp_f32_e32 v161, v94
	v_exp_f32_e32 v162, v95
	v_add_f32_e32 v252, v161, v252
	v_add_f32_e32 v252, v162, v252
	v_add_f32_e32 v217, v96, v252
	v_cvt_pk_bf16_f32 v100, v15, v100
	v_cvt_pk_bf16_f32 v101, v101, v102
	v_cvt_pk_bf16_f32 v102, v103, v104
	v_cvt_pk_bf16_f32 v103, v105, v106
	v_cvt_pk_bf16_f32 v248, v107, v108
	v_cvt_pk_bf16_f32 v249, v109, v110
	v_cvt_pk_bf16_f32 v250, v111, v160
	v_cvt_pk_bf16_f32 v251, v161, v162
	s_setprio 1
	s_waitcnt lgkmcnt(0)
	v_mfma_f32_32x32x16_bf16 v[64:79], v[2:5], v[100:103], v[64:79]
	v_mfma_f32_32x32x16_bf16 v[48:63], v[6:9], v[100:103], v[48:63]
	v_mfma_f32_32x32x16_bf16 v[32:47], v[10:13], v[100:103], v[32:47]
	v_mfma_f32_32x32x16_bf16 v[16:31], v[228:231], v[100:103], v[16:31]
	v_mfma_f32_32x32x16_bf16 v[64:79], v[232:235], v[248:251], v[64:79]
	v_mfma_f32_32x32x16_bf16 v[48:63], v[236:239], v[248:251], v[48:63]
	v_mfma_f32_32x32x16_bf16 v[32:47], v[240:243], v[248:251], v[32:47]
	v_mfma_f32_32x32x16_bf16 v[16:31], v[244:247], v[248:251], v[16:31]
	s_setprio 0
